# speedup vs baseline: 1.0053x; 1.0053x over previous
; #define BAR() __builtin_amdgcn_s_barrier()
; #define LDA(dst, b_, h_)                                                                                        \
;   _Pragma("unroll") for (int m = 0; m < 4; ++m) _Pragma("unroll") for (int k = 0; k < 2; ++k) dst[m][k] =       \
;       *(const bf16x8*)(smem + ((b_) * 2 + (h_)) * HT_B + lds_byte(wr0 * 64 + m * 16 + fr0, k * 32 + fq0 * 8))
; #define LDB(dst, b_, h_)                                                                                        \
;   _Pragma("unroll") for (int n = 0; n < 2; ++n) _Pragma("unroll") for (int k = 0; k < 2; ++k) dst[n][k] =       \
;       *(const bf16x8*)(smem + (4 + (b_) * 2 + (h_)) * HT_B + lds_byte(wc0 * 32 + n * 16 + fr0, k * 32 + fq0 * 8))
; #define WAIT_L(n) asm volatile("s_waitcnt lgkmcnt(" #n ")" ::: "memory")
; #define SCHED() __builtin_amdgcn_sched_barrier(0)
; __device__ __forceinline__ void gemm_phase(const GemmArgs& a, char* smem) {
;     ...
;       LDB(B0, 0, 0); SCHED(); LDA(At, 0, 0); STAGE_A(1, 1, t + 1);
;       WAIT_L(8); BAR(); WAIT_L(0); MMA(0, 0, At, B0); BAR(); SCHED();
;       LDB(B1, 0, 1); STAGE_B(0, 0, t + 2);
;       BAR(); WAIT_L(0); MMA(0, 1, At, B1); BAR();
;       LDA(At, 0, 1); STAGE_A(0, 0, t + 2);
;       BAR(); WAIT_L(0); MMA(1, 0, At, B0); BAR(); SCHED();
;       STAGE_B(0, 1, t + 2);
.LBB0_201:
	ds_read_b128 v[128:131], v179
	ds_read_b128 v[132:135], v179 offset:1024
	ds_read_b128 v[136:139], v179 offset:2048
	ds_read_b128 v[140:143], v179 offset:3072
	ds_read_b128 v[156:159], v180
	ds_read_b128 v[160:163], v180 offset:1024
	ds_read_b128 v[164:167], v181
	ds_read_b128 v[168:171], v181 offset:1024
	ds_read_b128 v[172:175], v182
	ds_read_b128 v[188:191], v182 offset:1024
	ds_read_b128 v[192:195], v183
	ds_read_b128 v[196:199], v183 offset:1024
	s_add_u32 s76, s88, s45
	s_addc_u32 s77, s89, s19
	s_mov_b32 s78, m0
	s_mov_b32 m0, s36
	s_nop 0
	global_load_lds_dwordx4 v187, s[76:77]
	s_mov_b32 m0, s78
	s_add_u32 s76, s88, s38
	s_addc_u32 s77, s89, s74
	s_mov_b32 s78, m0
	s_mov_b32 m0, s18
	s_nop 0
	global_load_lds_dwordx4 v187, s[76:77]
	s_mov_b32 m0, s78
	s_waitcnt lgkmcnt(8)
	s_barrier
	s_setprio 1
	s_waitcnt lgkmcnt(7)
	v_mfma_f32_16x16x32_bf16 v[124:127], v[128:131], v[156:159], v[124:127]
	v_mfma_f32_16x16x32_bf16 v[120:123], v[136:139], v[156:159], v[120:123]
	s_waitcnt lgkmcnt(5)
	v_mfma_f32_16x16x32_bf16 v[116:119], v[128:131], v[164:167], v[116:119]
	v_mfma_f32_16x16x32_bf16 v[112:115], v[136:139], v[164:167], v[112:115]
	s_waitcnt lgkmcnt(3)
	v_mfma_f32_16x16x32_bf16 v[108:111], v[128:131], v[172:175], v[108:111]
	v_mfma_f32_16x16x32_bf16 v[104:107], v[136:139], v[172:175], v[104:107]
	s_waitcnt lgkmcnt(1)
	v_mfma_f32_16x16x32_bf16 v[92:95], v[128:131], v[192:195], v[92:95]
	v_mfma_f32_16x16x32_bf16 v[76:79], v[136:139], v[192:195], v[76:79]
	v_mfma_f32_16x16x32_bf16 v[124:127], v[132:135], v[160:163], v[124:127]
	v_mfma_f32_16x16x32_bf16 v[120:123], v[140:143], v[160:163], v[120:123]
	v_mfma_f32_16x16x32_bf16 v[116:119], v[132:135], v[168:171], v[116:119]
	v_mfma_f32_16x16x32_bf16 v[112:115], v[140:143], v[168:171], v[112:115]
	v_mfma_f32_16x16x32_bf16 v[108:111], v[132:135], v[188:191], v[108:111]
	v_mfma_f32_16x16x32_bf16 v[104:107], v[140:143], v[188:191], v[104:107]
	s_waitcnt lgkmcnt(0)
	v_mfma_f32_16x16x32_bf16 v[92:95], v[132:135], v[196:199], v[92:95]
	v_mfma_f32_16x16x32_bf16 v[76:79], v[140:143], v[196:199], v[76:79]
	s_setprio 0
	s_barrier
	s_add_i32 s75, s75, 2
	s_add_u32 s78, s72, s10
	s_addc_u32 s79, s73, s11
	s_add_u32 s76, s78, 0x100
	ds_read_b128 v[200:203], v184
	ds_read_b128 v[204:207], v184 offset:1024
	ds_read_b128 v[218:221], v184 offset:2048
	ds_read_b128 v[222:225], v184 offset:3072
	s_addc_u32 s77, s79, 0
	s_mov_b32 s80, m0
	s_mov_b32 m0, s31
	s_nop 0
	global_load_lds_dwordx4 v178, s[76:77]
	s_mov_b32 m0, s80
	s_add_u32 s80, s72, vcc_lo
	s_addc_u32 s81, s73, vcc_hi
	s_add_u32 s76, s80, 0x100
	s_addc_u32 s77, s81, 0
	s_mov_b32 s84, m0
	s_mov_b32 m0, s4
	s_nop 0
	global_load_lds_dwordx4 v178, s[76:77]
	s_mov_b32 m0, s84
	s_barrier
	s_setprio 1
	s_waitcnt lgkmcnt(3)
	v_mfma_f32_16x16x32_bf16 v[28:31], v[200:203], v[156:159], v[28:31]
	s_waitcnt lgkmcnt(1)
	v_mfma_f32_16x16x32_bf16 v[24:27], v[218:221], v[156:159], v[24:27]
	v_mfma_f32_16x16x32_bf16 v[20:23], v[200:203], v[164:167], v[20:23]
	v_mfma_f32_16x16x32_bf16 v[16:19], v[218:221], v[164:167], v[16:19]
	v_mfma_f32_16x16x32_bf16 v[12:15], v[200:203], v[172:175], v[12:15]
	v_mfma_f32_16x16x32_bf16 v[8:11], v[218:221], v[172:175], v[8:11]
	v_mfma_f32_16x16x32_bf16 v[4:7], v[200:203], v[192:195], v[4:7]
	v_mfma_f32_16x16x32_bf16 v[0:3], v[218:221], v[192:195], v[0:3]
	v_mfma_f32_16x16x32_bf16 v[28:31], v[204:207], v[160:163], v[28:31]
	s_waitcnt lgkmcnt(0)
	v_mfma_f32_16x16x32_bf16 v[24:27], v[222:225], v[160:163], v[24:27]
	v_mfma_f32_16x16x32_bf16 v[20:23], v[204:207], v[168:171], v[20:23]
	v_mfma_f32_16x16x32_bf16 v[16:19], v[222:225], v[168:171], v[16:19]
	v_mfma_f32_16x16x32_bf16 v[12:15], v[204:207], v[188:191], v[12:15]
	v_mfma_f32_16x16x32_bf16 v[8:11], v[222:225], v[188:191], v[8:11]
	v_mfma_f32_16x16x32_bf16 v[4:7], v[204:207], v[196:199], v[4:7]
	v_mfma_f32_16x16x32_bf16 v[0:3], v[222:225], v[196:199], v[0:3]
	s_setprio 0
	s_barrier
	ds_read_b128 v[156:159], v180 offset:16384
	ds_read_b128 v[160:163], v180 offset:17408
	ds_read_b128 v[164:167], v181 offset:16384
	ds_read_b128 v[168:171], v181 offset:17408
	ds_read_b128 v[172:175], v182 offset:16384
	ds_read_b128 v[188:191], v182 offset:17408
	ds_read_b128 v[192:195], v183 offset:16384
	ds_read_b128 v[196:199], v183 offset:17408
	s_add_u32 s76, s88, s62
	s_addc_u32 s77, s89, s63
	s_mov_b32 s84, m0
	s_mov_b32 m0, s29
	s_nop 0
	global_load_lds_dwordx4 v187, s[76:77]
	s_mov_b32 m0, s84
	s_add_u32 s76, s88, s37
	s_addc_u32 s77, s89, s44
	s_mov_b32 s84, m0
	s_mov_b32 m0, s5
	s_nop 0
	global_load_lds_dwordx4 v187, s[76:77]
	s_mov_b32 m0, s84
	s_barrier
	s_setprio 1
	s_waitcnt lgkmcnt(7)
	v_mfma_f32_16x16x32_bf16 v[32:35], v[128:131], v[156:159], v[32:35]
	v_mfma_f32_16x16x32_bf16 v[36:39], v[136:139], v[156:159], v[36:39]
	s_waitcnt lgkmcnt(5)
	v_mfma_f32_16x16x32_bf16 v[40:43], v[128:131], v[164:167], v[40:43]
	v_mfma_f32_16x16x32_bf16 v[44:47], v[136:139], v[164:167], v[44:47]
	s_waitcnt lgkmcnt(3)
	v_mfma_f32_16x16x32_bf16 v[48:51], v[128:131], v[172:175], v[48:51]
	v_mfma_f32_16x16x32_bf16 v[52:55], v[136:139], v[172:175], v[52:55]
	s_waitcnt lgkmcnt(1)
	v_mfma_f32_16x16x32_bf16 v[60:63], v[128:131], v[192:195], v[60:63]
	v_mfma_f32_16x16x32_bf16 v[68:71], v[136:139], v[192:195], v[68:71]
	v_mfma_f32_16x16x32_bf16 v[32:35], v[132:135], v[160:163], v[32:35]
	v_mfma_f32_16x16x32_bf16 v[36:39], v[140:143], v[160:163], v[36:39]
	v_mfma_f32_16x16x32_bf16 v[40:43], v[132:135], v[168:171], v[40:43]
	v_mfma_f32_16x16x32_bf16 v[44:47], v[140:143], v[168:171], v[44:47]
	v_mfma_f32_16x16x32_bf16 v[48:51], v[132:135], v[188:191], v[48:51]
	v_mfma_f32_16x16x32_bf16 v[52:55], v[140:143], v[188:191], v[52:55]
	s_waitcnt lgkmcnt(0)
	v_mfma_f32_16x16x32_bf16 v[60:63], v[132:135], v[196:199], v[60:63]
	v_mfma_f32_16x16x32_bf16 v[68:71], v[140:143], v[196:199], v[68:71]
	s_setprio 0
	s_barrier
; #define WAIT_V(n) asm volatile("s_waitcnt vmcnt(" #n ")" ::: "memory")
; #define BAR() __builtin_amdgcn_s_barrier()
; #define LDA(dst, b_, h_)                                                                                        \
;   _Pragma("unroll") for (int m = 0; m < 4; ++m) _Pragma("unroll") for (int k = 0; k < 2; ++k) dst[m][k] =       \
;       *(const bf16x8*)(smem + ((b_) * 2 + (h_)) * HT_B + lds_byte(wr0 * 64 + m * 16 + fr0, k * 32 + fq0 * 8))
; #define LDB(dst, b_, h_)                                                                                        \
;   _Pragma("unroll") for (int n = 0; n < 2; ++n) _Pragma("unroll") for (int k = 0; k < 2; ++k) dst[n][k] =       \
;       *(const bf16x8*)(smem + (4 + (b_) * 2 + (h_)) * HT_B + lds_byte(wc0 * 32 + n * 16 + fr0, k * 32 + fq0 * 8))
; #define WAIT_L(n) asm volatile("s_waitcnt lgkmcnt(" #n ")" ::: "memory")
; #define SCHED() __builtin_amdgcn_sched_barrier(0)
; __device__ __forceinline__ void gemm_phase(const GemmArgs& a, char* smem) {
;     ...
;       WAIT_V(6); BAR(); MMA(1, 1, At, B1); BAR();
;       LDB(B0, 1, 0); SCHED(); LDA(At, 1, 0); STAGE_A(0, 1, t + 2);
;       WAIT_L(8); BAR(); WAIT_L(0); MMA(0, 0, At, B0); BAR(); SCHED();
;       LDB(B1, 1, 1); STAGE_B(1, 0, t + 3);
;       BAR(); WAIT_L(0); MMA(0, 1, At, B1); BAR();
;       LDA(At, 1, 1); STAGE_A(1, 0, t + 3);
	s_add_u32 s84, s72, s50
	s_addc_u32 s85, s73, s51
	s_add_u32 s76, s84, 0x100
	s_addc_u32 s77, s85, 0
	s_mov_b32 s86, m0
	s_mov_b32 m0, s0
	s_nop 0
	global_load_lds_dwordx4 v178, s[76:77]
	s_mov_b32 m0, s86
	s_add_u32 s86, s72, s68
	s_addc_u32 s87, s73, s69
	s_add_u32 s76, s86, 0x100
	s_addc_u32 s77, s87, 0
	s_mov_b32 s30, m0
	s_mov_b32 m0, s1
	s_nop 0
	global_load_lds_dwordx4 v178, s[76:77]
	s_mov_b32 m0, s30
	s_waitcnt vmcnt(6)
	s_barrier
	s_setprio 1
	v_mfma_f32_16x16x32_bf16 v[56:59], v[200:203], v[156:159], v[56:59]
	v_mfma_f32_16x16x32_bf16 v[64:67], v[218:221], v[156:159], v[64:67]
	v_mfma_f32_16x16x32_bf16 v[72:75], v[200:203], v[164:167], v[72:75]
	v_mfma_f32_16x16x32_bf16 v[80:83], v[218:221], v[164:167], v[80:83]
	v_mfma_f32_16x16x32_bf16 v[84:87], v[200:203], v[172:175], v[84:87]
	v_mfma_f32_16x16x32_bf16 v[88:91], v[218:221], v[172:175], v[88:91]
	v_mfma_f32_16x16x32_bf16 v[96:99], v[200:203], v[192:195], v[96:99]
	v_mfma_f32_16x16x32_bf16 v[100:103], v[218:221], v[192:195], v[100:103]
	v_mfma_f32_16x16x32_bf16 v[56:59], v[204:207], v[160:163], v[56:59]
	v_mfma_f32_16x16x32_bf16 v[64:67], v[222:225], v[160:163], v[64:67]
	v_mfma_f32_16x16x32_bf16 v[72:75], v[204:207], v[168:171], v[72:75]
	v_mfma_f32_16x16x32_bf16 v[80:83], v[222:225], v[168:171], v[80:83]
	v_mfma_f32_16x16x32_bf16 v[84:87], v[204:207], v[188:191], v[84:87]
	v_mfma_f32_16x16x32_bf16 v[88:91], v[222:225], v[188:191], v[88:91]
	v_mfma_f32_16x16x32_bf16 v[96:99], v[204:207], v[196:199], v[96:99]
	v_mfma_f32_16x16x32_bf16 v[100:103], v[222:225], v[196:199], v[100:103]
	s_setprio 0
	s_barrier
	ds_read_b128 v[128:131], v185
	ds_read_b128 v[132:135], v185 offset:1024
	ds_read_b128 v[136:139], v185 offset:2048
	ds_read_b128 v[140:143], v185 offset:3072
	ds_read_b128 v[156:159], v180 offset:32768
	ds_read_b128 v[160:163], v180 offset:33792
	ds_read_b128 v[164:167], v181 offset:32768
	ds_read_b128 v[168:171], v181 offset:33792
	ds_read_b128 v[172:175], v182 offset:32768
	ds_read_b128 v[188:191], v182 offset:33792
	ds_read_b128 v[192:195], v183 offset:32768
	ds_read_b128 v[196:199], v183 offset:33792
	s_add_u32 s76, s88, s22
	s_addc_u32 s77, s89, s23
	s_mov_b32 s30, m0
	s_mov_b32 m0, s16
	s_nop 0
	global_load_lds_dwordx4 v187, s[76:77]
	s_mov_b32 m0, s30
	s_add_u32 s76, s88, s2
	s_addc_u32 s77, s89, s3
	s_mov_b32 s30, m0
	s_mov_b32 m0, s17
	s_nop 0
	global_load_lds_dwordx4 v187, s[76:77]
	s_mov_b32 m0, s30
	s_waitcnt lgkmcnt(8)
	s_barrier
	s_setprio 1
	s_waitcnt lgkmcnt(7)
	v_mfma_f32_16x16x32_bf16 v[124:127], v[128:131], v[156:159], v[124:127]
	v_mfma_f32_16x16x32_bf16 v[120:123], v[136:139], v[156:159], v[120:123]
	s_waitcnt lgkmcnt(5)
	v_mfma_f32_16x16x32_bf16 v[116:119], v[128:131], v[164:167], v[116:119]
	v_mfma_f32_16x16x32_bf16 v[112:115], v[136:139], v[164:167], v[112:115]
	s_waitcnt lgkmcnt(3)
	v_mfma_f32_16x16x32_bf16 v[108:111], v[128:131], v[172:175], v[108:111]
	v_mfma_f32_16x16x32_bf16 v[104:107], v[136:139], v[172:175], v[104:107]
	s_waitcnt lgkmcnt(1)
	v_mfma_f32_16x16x32_bf16 v[92:95], v[128:131], v[192:195], v[92:95]
	v_mfma_f32_16x16x32_bf16 v[76:79], v[136:139], v[192:195], v[76:79]
	v_mfma_f32_16x16x32_bf16 v[124:127], v[132:135], v[160:163], v[124:127]
	v_mfma_f32_16x16x32_bf16 v[120:123], v[140:143], v[160:163], v[120:123]
	v_mfma_f32_16x16x32_bf16 v[116:119], v[132:135], v[168:171], v[116:119]
	v_mfma_f32_16x16x32_bf16 v[112:115], v[140:143], v[168:171], v[112:115]
	v_mfma_f32_16x16x32_bf16 v[108:111], v[132:135], v[188:191], v[108:111]
	v_mfma_f32_16x16x32_bf16 v[104:107], v[140:143], v[188:191], v[104:107]
	s_waitcnt lgkmcnt(0)
	v_mfma_f32_16x16x32_bf16 v[92:95], v[132:135], v[196:199], v[92:95]
	v_mfma_f32_16x16x32_bf16 v[76:79], v[140:143], v[196:199], v[76:79]
	s_setprio 0
	s_barrier
	ds_read_b128 v[200:203], v186
	ds_read_b128 v[204:207], v186 offset:1024
	ds_read_b128 v[218:221], v186 offset:2048
	ds_read_b128 v[222:225], v186 offset:3072
	s_add_u32 s76, s78, 0x180
	s_addc_u32 s77, s79, 0
	s_mov_b32 s30, m0
	s_mov_b32 m0, s13
	s_nop 0
	global_load_lds_dwordx4 v178, s[76:77]
	s_mov_b32 m0, s30
	s_add_u32 s76, s80, 0x180
	s_addc_u32 s77, s81, 0
	s_mov_b32 s30, m0
	s_mov_b32 m0, s26
	s_nop 0
	global_load_lds_dwordx4 v178, s[76:77]
	s_mov_b32 m0, s30
	s_barrier
	s_setprio 1
	s_waitcnt lgkmcnt(3)
	v_mfma_f32_16x16x32_bf16 v[28:31], v[200:203], v[156:159], v[28:31]
	s_waitcnt lgkmcnt(1)
	v_mfma_f32_16x16x32_bf16 v[24:27], v[218:221], v[156:159], v[24:27]
	v_mfma_f32_16x16x32_bf16 v[20:23], v[200:203], v[164:167], v[20:23]
	v_mfma_f32_16x16x32_bf16 v[16:19], v[218:221], v[164:167], v[16:19]
	v_mfma_f32_16x16x32_bf16 v[12:15], v[200:203], v[172:175], v[12:15]
	v_mfma_f32_16x16x32_bf16 v[8:11], v[218:221], v[172:175], v[8:11]
	v_mfma_f32_16x16x32_bf16 v[4:7], v[200:203], v[192:195], v[4:7]
	v_mfma_f32_16x16x32_bf16 v[0:3], v[218:221], v[192:195], v[0:3]
	v_mfma_f32_16x16x32_bf16 v[28:31], v[204:207], v[160:163], v[28:31]
	s_waitcnt lgkmcnt(0)
	v_mfma_f32_16x16x32_bf16 v[24:27], v[222:225], v[160:163], v[24:27]
	v_mfma_f32_16x16x32_bf16 v[20:23], v[204:207], v[168:171], v[20:23]
	v_mfma_f32_16x16x32_bf16 v[16:19], v[222:225], v[168:171], v[16:19]
	v_mfma_f32_16x16x32_bf16 v[12:15], v[204:207], v[188:191], v[12:15]
	v_mfma_f32_16x16x32_bf16 v[8:11], v[222:225], v[188:191], v[8:11]
	v_mfma_f32_16x16x32_bf16 v[4:7], v[204:207], v[196:199], v[4:7]
	v_mfma_f32_16x16x32_bf16 v[0:3], v[222:225], v[196:199], v[0:3]
	s_setprio 0
	s_barrier
; #define WAIT_V(n) asm volatile("s_waitcnt vmcnt(" #n ")" ::: "memory")
; #define BAR() __builtin_amdgcn_s_barrier()
; #define LDA(dst, b_, h_)                                                                                        \
;   _Pragma("unroll") for (int m = 0; m < 4; ++m) _Pragma("unroll") for (int k = 0; k < 2; ++k) dst[m][k] =       \
;       *(const bf16x8*)(smem + ((b_) * 2 + (h_)) * HT_B + lds_byte(wr0 * 64 + m * 16 + fr0, k * 32 + fq0 * 8))
; #define LDB(dst, b_, h_)                                                                                        \
;   _Pragma("unroll") for (int n = 0; n < 2; ++n) _Pragma("unroll") for (int k = 0; k < 2; ++k) dst[n][k] =       \
;       *(const bf16x8*)(smem + (4 + (b_) * 2 + (h_)) * HT_B + lds_byte(wc0 * 32 + n * 16 + fr0, k * 32 + fq0 * 8))
; #define WAIT_L(n) asm volatile("s_waitcnt lgkmcnt(" #n ")" ::: "memory")
; #define SCHED() __builtin_amdgcn_sched_barrier(0)
; __device__ __forceinline__ void gemm_phase(const GemmArgs& a, char* smem) {
;     ...
;       BAR(); WAIT_L(0); MMA(1, 0, At, B0); BAR(); SCHED();
;       STAGE_B(1, 1, t + 3);
;       WAIT_V(6); BAR(); MMA(1, 1, At, B1); BAR();
;     }
;     {
;       LDB(B0, 0, 0); LDA(At, 0, 0); STAGE_A(1, 1, nt - 1);
	ds_read_b128 v[156:159], v180 offset:49152
	ds_read_b128 v[160:163], v180 offset:50176
	ds_read_b128 v[164:167], v181 offset:49152
	ds_read_b128 v[168:171], v181 offset:50176
	ds_read_b128 v[172:175], v182 offset:49152
	ds_read_b128 v[188:191], v182 offset:50176
	ds_read_b128 v[192:195], v183 offset:49152
	ds_read_b128 v[196:199], v183 offset:50176
	s_add_u32 s76, s88, s15
	s_addc_u32 s77, s89, s12
	s_mov_b32 s30, m0
	s_mov_b32 m0, s27
	s_nop 0
	global_load_lds_dwordx4 v187, s[76:77]
	s_mov_b32 m0, s30
	s_add_u32 s76, s88, s57
	s_addc_u32 s77, s89, s90
	s_mov_b32 s30, m0
	s_mov_b32 m0, s24
	s_nop 0
	global_load_lds_dwordx4 v187, s[76:77]
	s_mov_b32 m0, s30
	s_barrier
	s_setprio 1
	s_waitcnt lgkmcnt(7)
	v_mfma_f32_16x16x32_bf16 v[32:35], v[128:131], v[156:159], v[32:35]
	v_mfma_f32_16x16x32_bf16 v[36:39], v[136:139], v[156:159], v[36:39]
	s_waitcnt lgkmcnt(5)
	v_mfma_f32_16x16x32_bf16 v[40:43], v[128:131], v[164:167], v[40:43]
	v_mfma_f32_16x16x32_bf16 v[44:47], v[136:139], v[164:167], v[44:47]
	s_waitcnt lgkmcnt(3)
	v_mfma_f32_16x16x32_bf16 v[48:51], v[128:131], v[172:175], v[48:51]
	v_mfma_f32_16x16x32_bf16 v[52:55], v[136:139], v[172:175], v[52:55]
	s_waitcnt lgkmcnt(1)
	v_mfma_f32_16x16x32_bf16 v[60:63], v[128:131], v[192:195], v[60:63]
	v_mfma_f32_16x16x32_bf16 v[68:71], v[136:139], v[192:195], v[68:71]
	v_mfma_f32_16x16x32_bf16 v[32:35], v[132:135], v[160:163], v[32:35]
	v_mfma_f32_16x16x32_bf16 v[36:39], v[140:143], v[160:163], v[36:39]
	v_mfma_f32_16x16x32_bf16 v[40:43], v[132:135], v[168:171], v[40:43]
	v_mfma_f32_16x16x32_bf16 v[44:47], v[140:143], v[168:171], v[44:47]
	v_mfma_f32_16x16x32_bf16 v[48:51], v[132:135], v[188:191], v[48:51]
	v_mfma_f32_16x16x32_bf16 v[52:55], v[140:143], v[188:191], v[52:55]
	s_waitcnt lgkmcnt(0)
	v_mfma_f32_16x16x32_bf16 v[60:63], v[132:135], v[196:199], v[60:63]
	v_mfma_f32_16x16x32_bf16 v[68:71], v[140:143], v[196:199], v[68:71]
	s_setprio 0
	s_barrier
	s_add_u32 s76, s84, 0x180
	s_addc_u32 s77, s85, 0
	s_mov_b32 s30, m0
	s_mov_b32 m0, s25
	s_nop 0
	global_load_lds_dwordx4 v178, s[76:77]
	s_mov_b32 m0, s30
	s_add_u32 s76, s86, 0x180
	s_addc_u32 s77, s87, 0
	s_mov_b32 s30, m0
	s_mov_b32 m0, s34
	s_nop 0
	global_load_lds_dwordx4 v178, s[76:77]
	s_mov_b32 m0, s30
	s_add_u32 s57, s57, s8
	s_addc_u32 s90, s90, s9
	s_add_u32 s15, s15, s8
	s_addc_u32 s12, s12, s9
	s_add_u32 s50, s50, 0x100
	s_addc_u32 s51, s51, 0
	s_add_u32 s68, s68, 0x100
	s_addc_u32 s69, s69, 0
	s_add_u32 vcc_lo, vcc_lo, 0x100
	s_addc_u32 vcc_hi, vcc_hi, 0
	s_add_u32 s10, s10, 0x100
	s_addc_u32 s11, s11, 0
	s_add_u32 s2, s2, s8
	s_addc_u32 s3, s3, s9
	s_add_u32 s22, s22, s8
	s_addc_u32 s23, s23, s9
	s_add_u32 s37, s37, s8
	s_addc_u32 s44, s44, s9
	s_add_u32 s62, s62, s8
	s_addc_u32 s63, s63, s9
	s_add_u32 s38, s38, s8
	s_addc_u32 s74, s74, s9
	s_add_u32 s45, s45, s8
	s_addc_u32 s19, s19, s9
	s_waitcnt vmcnt(6)
	s_barrier
	s_setprio 1
	v_mfma_f32_16x16x32_bf16 v[56:59], v[200:203], v[156:159], v[56:59]
	v_mfma_f32_16x16x32_bf16 v[64:67], v[218:221], v[156:159], v[64:67]
	v_mfma_f32_16x16x32_bf16 v[72:75], v[200:203], v[164:167], v[72:75]
	v_mfma_f32_16x16x32_bf16 v[80:83], v[218:221], v[164:167], v[80:83]
	v_mfma_f32_16x16x32_bf16 v[84:87], v[200:203], v[172:175], v[84:87]
	v_mfma_f32_16x16x32_bf16 v[88:91], v[218:221], v[172:175], v[88:91]
	v_mfma_f32_16x16x32_bf16 v[96:99], v[200:203], v[192:195], v[96:99]
	v_mfma_f32_16x16x32_bf16 v[100:103], v[218:221], v[192:195], v[100:103]
	v_mfma_f32_16x16x32_bf16 v[56:59], v[204:207], v[160:163], v[56:59]
	v_mfma_f32_16x16x32_bf16 v[64:67], v[222:225], v[160:163], v[64:67]
	v_mfma_f32_16x16x32_bf16 v[72:75], v[204:207], v[168:171], v[72:75]
	v_mfma_f32_16x16x32_bf16 v[80:83], v[222:225], v[168:171], v[80:83]
	v_mfma_f32_16x16x32_bf16 v[84:87], v[204:207], v[188:191], v[84:87]
	v_mfma_f32_16x16x32_bf16 v[88:91], v[222:225], v[188:191], v[88:91]
	v_mfma_f32_16x16x32_bf16 v[96:99], v[204:207], v[196:199], v[96:99]
	v_mfma_f32_16x16x32_bf16 v[100:103], v[222:225], v[196:199], v[100:103]
	s_setprio 0
	s_cmp_ge_u32 s75, s35
	s_barrier
	s_cbranch_scc0 .LBB0_201
	ds_read_b128 v[128:131], v179
	ds_read_b128 v[132:135], v179 offset:1024
	ds_read_b128 v[136:139], v179 offset:2048
	ds_read_b128 v[140:143], v179 offset:3072
	ds_read_b128 v[156:159], v180
	ds_read_b128 v[160:163], v180 offset:1024
	ds_read_b128 v[164:167], v181
	ds_read_b128 v[168:171], v181 offset:1024
	ds_read_b128 v[172:175], v182
	ds_read_b128 v[188:191], v182 offset:1024
	ds_read_b128 v[192:195], v183
	ds_read_b128 v[196:199], v183 offset:1024
	v_readlane_b32 s8, v250, 9
	s_mul_i32 s2, s43, s8
	s_mul_hi_u32 s3, s42, s8
	s_add_i32 s3, s3, s2
	s_mul_i32 s2, s42, s8
	s_add_u32 s2, s88, s2
	s_addc_u32 s3, s89, s3
	s_add_u32 s2, s2, s96
	s_addc_u32 s3, s3, s97
	s_mov_b32 s8, m0
	s_mov_b32 m0, s36
	s_nop 0
	global_load_lds_dwordx4 v187, s[2:3]
	s_mov_b32 m0, s8
	s_add_u32 s2, s2, s6
	s_addc_u32 s3, s3, s7
	s_mov_b32 s6, m0
	s_mov_b32 m0, s18
	s_nop 0
	global_load_lds_dwordx4 v187, s[2:3]
	s_mov_b32 m0, s6
	s_barrier
; #define WAIT_V(n) asm volatile("s_waitcnt vmcnt(" #n ")" ::: "memory")
; #define BAR() __builtin_amdgcn_s_barrier()
; #define LDA(dst, b_, h_)                                                                                        \
;   _Pragma("unroll") for (int m = 0; m < 4; ++m) _Pragma("unroll") for (int k = 0; k < 2; ++k) dst[m][k] =       \
;       *(const bf16x8*)(smem + ((b_) * 2 + (h_)) * HT_B + lds_byte(wr0 * 64 + m * 16 + fr0, k * 32 + fq0 * 8))
; #define LDB(dst, b_, h_)                                                                                        \
;   _Pragma("unroll") for (int n = 0; n < 2; ++n) _Pragma("unroll") for (int k = 0; k < 2; ++k) dst[n][k] =       \
;       *(const bf16x8*)(smem + (4 + (b_) * 2 + (h_)) * HT_B + lds_byte(wc0 * 32 + n * 16 + fr0, k * 32 + fq0 * 8))
; #define WAIT_L(n) asm volatile("s_waitcnt lgkmcnt(" #n ")" ::: "memory")
; #define SCHED() __builtin_amdgcn_sched_barrier(0)
; __device__ __forceinline__ void gemm_phase(const GemmArgs& a, char* smem) {
;     ...
;       LDB(B0, 0, 0); LDA(At, 0, 0); STAGE_A(1, 1, nt - 1);
;       BAR(); WAIT_L(0); MMA(0, 0, At, B0); BAR(); SCHED();
;       LDB(B1, 0, 1); BAR(); WAIT_L(0); MMA(0, 1, At, B1); BAR(); SCHED();
;       LDA(At, 0, 1); WAIT_V(4); BAR(); WAIT_L(0); MMA(1, 0, At, B0); MMA(1, 1, At, B1); BAR(); SCHED();
	s_waitcnt lgkmcnt(0)
	s_setprio 1
	s_waitcnt lgkmcnt(7)
	v_mfma_f32_16x16x32_bf16 v[124:127], v[128:131], v[156:159], v[124:127]
	v_mfma_f32_16x16x32_bf16 v[120:123], v[136:139], v[156:159], v[120:123]
	s_waitcnt lgkmcnt(3)
	v_mfma_f32_16x16x32_bf16 v[108:111], v[128:131], v[172:175], v[108:111]
	v_mfma_f32_16x16x32_bf16 v[104:107], v[136:139], v[172:175], v[104:107]
	s_waitcnt lgkmcnt(1)
	v_mfma_f32_16x16x32_bf16 v[92:95], v[128:131], v[192:195], v[92:95]
	v_mfma_f32_16x16x32_bf16 v[76:79], v[136:139], v[192:195], v[76:79]
	v_mfma_f32_16x16x32_bf16 v[124:127], v[132:135], v[160:163], v[124:127]
	v_mfma_f32_16x16x32_bf16 v[120:123], v[140:143], v[160:163], v[120:123]
	v_mfma_f32_16x16x32_bf16 v[116:119], v[128:131], v[164:167], v[116:119]
	v_mfma_f32_16x16x32_bf16 v[112:115], v[136:139], v[164:167], v[112:115]
	v_mfma_f32_16x16x32_bf16 v[108:111], v[132:135], v[188:191], v[108:111]
	v_mfma_f32_16x16x32_bf16 v[104:107], v[140:143], v[188:191], v[104:107]
	s_waitcnt lgkmcnt(0)
	v_mfma_f32_16x16x32_bf16 v[92:95], v[132:135], v[196:199], v[92:95]
	v_mfma_f32_16x16x32_bf16 v[76:79], v[140:143], v[196:199], v[76:79]
	v_mfma_f32_16x16x32_bf16 v[200:203], v[132:135], v[168:171], v[116:119]
	v_mfma_f32_16x16x32_bf16 v[204:207], v[140:143], v[168:171], v[112:115]
	s_setprio 0
	s_barrier
	s_nop 0
	ds_read_b128 v[112:115], v184
	ds_read_b128 v[116:119], v184 offset:1024
	ds_read_b128 v[218:221], v184 offset:2048
	ds_read_b128 v[222:225], v184 offset:3072
	s_barrier
	s_waitcnt lgkmcnt(0)
	s_setprio 1
	s_waitcnt lgkmcnt(3)
	v_mfma_f32_16x16x32_bf16 v[28:31], v[112:115], v[156:159], v[28:31]
	s_waitcnt lgkmcnt(1)
	v_mfma_f32_16x16x32_bf16 v[24:27], v[218:221], v[156:159], v[24:27]
	v_mfma_f32_16x16x32_bf16 v[20:23], v[112:115], v[164:167], v[20:23]
	v_mfma_f32_16x16x32_bf16 v[16:19], v[218:221], v[164:167], v[16:19]
	v_mfma_f32_16x16x32_bf16 v[12:15], v[112:115], v[172:175], v[12:15]
	v_mfma_f32_16x16x32_bf16 v[8:11], v[218:221], v[172:175], v[8:11]
	v_mfma_f32_16x16x32_bf16 v[4:7], v[112:115], v[192:195], v[4:7]
	v_mfma_f32_16x16x32_bf16 v[0:3], v[218:221], v[192:195], v[0:3]
	v_mfma_f32_16x16x32_bf16 v[28:31], v[116:119], v[160:163], v[28:31]
	s_waitcnt lgkmcnt(0)
	v_mfma_f32_16x16x32_bf16 v[24:27], v[222:225], v[160:163], v[24:27]
	v_mfma_f32_16x16x32_bf16 v[20:23], v[116:119], v[168:171], v[20:23]
	v_mfma_f32_16x16x32_bf16 v[16:19], v[222:225], v[168:171], v[16:19]
	v_mfma_f32_16x16x32_bf16 v[12:15], v[116:119], v[188:191], v[12:15]
	v_mfma_f32_16x16x32_bf16 v[8:11], v[222:225], v[188:191], v[8:11]
	v_mfma_f32_16x16x32_bf16 v[4:7], v[116:119], v[196:199], v[4:7]
	v_mfma_f32_16x16x32_bf16 v[0:3], v[222:225], v[196:199], v[0:3]
	s_setprio 0
	s_barrier
	ds_read_b128 v[156:159], v180 offset:16384
	ds_read_b128 v[160:163], v180 offset:17408
	ds_read_b128 v[164:167], v181 offset:16384
	ds_read_b128 v[168:171], v181 offset:17408
	ds_read_b128 v[172:175], v182 offset:16384
	ds_read_b128 v[188:191], v182 offset:17408
	ds_read_b128 v[192:195], v183 offset:16384
	ds_read_b128 v[196:199], v183 offset:17408
	s_waitcnt vmcnt(4)
	s_barrier
	s_waitcnt lgkmcnt(0)
	s_setprio 1
	s_waitcnt lgkmcnt(3)
	v_mfma_f32_16x16x32_bf16 v[48:51], v[128:131], v[172:175], v[48:51]
	s_waitcnt lgkmcnt(2)
	v_mfma_f32_16x16x32_bf16 v[226:229], v[132:135], v[188:191], v[48:51]
	v_mfma_f32_16x16x32_bf16 v[48:51], v[136:139], v[172:175], v[52:55]
	v_mfma_f32_16x16x32_bf16 v[32:35], v[128:131], v[156:159], v[32:35]
	v_mfma_f32_16x16x32_bf16 v[36:39], v[136:139], v[156:159], v[36:39]
	v_mfma_f32_16x16x32_bf16 v[40:43], v[128:131], v[164:167], v[40:43]
	v_mfma_f32_16x16x32_bf16 v[44:47], v[136:139], v[164:167], v[44:47]
	v_mfma_f32_16x16x32_bf16 v[230:233], v[140:143], v[188:191], v[48:51]
	s_waitcnt lgkmcnt(1)
	v_mfma_f32_16x16x32_bf16 v[48:51], v[128:131], v[192:195], v[60:63]
	v_mfma_f32_16x16x32_bf16 v[32:35], v[132:135], v[160:163], v[32:35]
	v_mfma_f32_16x16x32_bf16 v[36:39], v[140:143], v[160:163], v[36:39]
	v_mfma_f32_16x16x32_bf16 v[40:43], v[132:135], v[168:171], v[40:43]
	v_mfma_f32_16x16x32_bf16 v[44:47], v[140:143], v[168:171], v[44:47]
	s_waitcnt lgkmcnt(0)
	v_mfma_f32_16x16x32_bf16 v[60:63], v[132:135], v[196:199], v[48:51]
	v_mfma_f32_16x16x32_bf16 v[48:51], v[136:139], v[192:195], v[68:71]
	v_mfma_f32_16x16x32_bf16 v[128:131], v[140:143], v[196:199], v[48:51]
	s_setprio 0
	s_setprio 1
	v_mfma_f32_16x16x32_bf16 v[48:51], v[112:115], v[156:159], v[56:59]
	v_mfma_f32_16x16x32_bf16 v[56:59], v[116:119], v[160:163], v[48:51]
	v_mfma_f32_16x16x32_bf16 v[48:51], v[218:221], v[156:159], v[64:67]
	v_mfma_f32_16x16x32_bf16 v[132:135], v[222:225], v[160:163], v[48:51]
	v_mfma_f32_16x16x32_bf16 v[48:51], v[112:115], v[164:167], v[72:75]
	v_mfma_f32_16x16x32_bf16 v[136:139], v[116:119], v[168:171], v[48:51]
	v_mfma_f32_16x16x32_bf16 v[48:51], v[218:221], v[164:167], v[80:83]
	v_mfma_f32_16x16x32_bf16 v[140:143], v[222:225], v[168:171], v[48:51]
	v_mfma_f32_16x16x32_bf16 v[48:51], v[112:115], v[172:175], v[84:87]
	v_mfma_f32_16x16x32_bf16 v[156:159], v[116:119], v[188:191], v[48:51]
	v_mfma_f32_16x16x32_bf16 v[48:51], v[218:221], v[172:175], v[88:91]
	v_mfma_f32_16x16x32_bf16 v[160:163], v[222:225], v[188:191], v[48:51]
	v_mfma_f32_16x16x32_bf16 v[48:51], v[112:115], v[192:195], v[96:99]
	v_mfma_f32_16x16x32_bf16 v[164:167], v[116:119], v[196:199], v[48:51]
	v_mfma_f32_16x16x32_bf16 v[48:51], v[218:221], v[192:195], v[100:103]
	v_mfma_f32_16x16x32_bf16 v[168:171], v[222:225], v[196:199], v[48:51]
	s_setprio 0
	s_barrier
; #define WAIT_V(n) asm volatile("s_waitcnt vmcnt(" #n ")" ::: "memory")
; #define BAR() __builtin_amdgcn_s_barrier()
; #define LDA(dst, b_, h_)                                                                                        \
;   _Pragma("unroll") for (int m = 0; m < 4; ++m) _Pragma("unroll") for (int k = 0; k < 2; ++k) dst[m][k] =       \
;       *(const bf16x8*)(smem + ((b_) * 2 + (h_)) * HT_B + lds_byte(wr0 * 64 + m * 16 + fr0, k * 32 + fq0 * 8))
; #define LDB(dst, b_, h_)                                                                                        \
;   _Pragma("unroll") for (int n = 0; n < 2; ++n) _Pragma("unroll") for (int k = 0; k < 2; ++k) dst[n][k] =       \
;       *(const bf16x8*)(smem + (4 + (b_) * 2 + (h_)) * HT_B + lds_byte(wc0 * 32 + n * 16 + fr0, k * 32 + fq0 * 8))
; #define WAIT_L(n) asm volatile("s_waitcnt lgkmcnt(" #n ")" ::: "memory")
; #define SCHED() __builtin_amdgcn_sched_barrier(0)
; __device__ __forceinline__ void gemm_phase(const GemmArgs& a, char* smem) {
;     ...
;       LDB(B0, 1, 0); LDA(At, 1, 0); WAIT_V(2); BAR(); WAIT_L(0); MMA(0, 0, At, B0); BAR(); SCHED();
;       LDB(B1, 1, 1); WAIT_V(0); BAR(); WAIT_L(0); MMA(0, 1, At, B1); BAR(); SCHED();
;       LDA(At, 1, 1); BAR(); WAIT_L(0); MMA(1, 0, At, B0); MMA(1, 1, At, B1); BAR(); SCHED();
;     }
;     if (wr0 == 0) BAR();
	ds_read_b128 v[172:175], v185
	ds_read_b128 v[188:191], v185 offset:1024
	ds_read_b128 v[192:195], v185 offset:2048
	ds_read_b128 v[196:199], v185 offset:3072
	s_nop 0
	ds_read_b128 v[48:51], v180 offset:32768
	ds_read_b128 v[52:55], v180 offset:33792
	ds_read_b128 v[72:75], v181 offset:32768
	ds_read_b128 v[88:91], v181 offset:33792
	ds_read_b128 v[218:221], v182 offset:32768
	ds_read_b128 v[222:225], v182 offset:33792
	ds_read_b128 v[234:237], v183 offset:32768
	ds_read_b128 v[238:241], v183 offset:33792
	s_waitcnt vmcnt(2)
	s_barrier
	s_waitcnt lgkmcnt(0)
	s_setprio 1
	s_waitcnt lgkmcnt(7)
	v_mfma_f32_16x16x32_bf16 v[64:67], v[172:175], v[48:51], v[124:127]
	s_waitcnt lgkmcnt(6)
	v_mfma_f32_16x16x32_bf16 v[116:119], v[188:191], v[52:55], v[64:67]
	v_mfma_f32_16x16x32_bf16 v[64:67], v[192:195], v[48:51], v[120:123]
	v_mfma_f32_16x16x32_bf16 v[112:115], v[196:199], v[52:55], v[64:67]
	s_waitcnt lgkmcnt(5)
	v_mfma_f32_16x16x32_bf16 v[64:67], v[172:175], v[72:75], v[200:203]
	s_waitcnt lgkmcnt(4)
	v_mfma_f32_16x16x32_bf16 v[96:99], v[188:191], v[88:91], v[64:67]
	v_mfma_f32_16x16x32_bf16 v[64:67], v[192:195], v[72:75], v[204:207]
	v_mfma_f32_16x16x32_bf16 v[100:103], v[196:199], v[88:91], v[64:67]
	s_waitcnt lgkmcnt(3)
	v_mfma_f32_16x16x32_bf16 v[64:67], v[172:175], v[218:221], v[108:111]
	s_waitcnt lgkmcnt(2)
	v_mfma_f32_16x16x32_bf16 v[80:83], v[188:191], v[222:225], v[64:67]
	v_mfma_f32_16x16x32_bf16 v[64:67], v[192:195], v[218:221], v[104:107]
	v_mfma_f32_16x16x32_bf16 v[84:87], v[196:199], v[222:225], v[64:67]
	s_waitcnt lgkmcnt(1)
	v_mfma_f32_16x16x32_bf16 v[64:67], v[172:175], v[234:237], v[92:95]
	v_mfma_f32_16x16x32_bf16 v[68:71], v[192:195], v[234:237], v[76:79]
	s_waitcnt lgkmcnt(0)
	v_mfma_f32_16x16x32_bf16 v[64:67], v[188:191], v[238:241], v[64:67]
	v_mfma_f32_16x16x32_bf16 v[68:71], v[196:199], v[238:241], v[68:71]
	s_setprio 0
	s_barrier
	ds_read_b128 v[200:203], v186
	ds_read_b128 v[204:207], v186 offset:1024
	ds_read_b128 v[242:245], v186 offset:2048
	ds_read_b128 v[246:249], v186 offset:3072
	s_waitcnt vmcnt(0)
	s_barrier
	s_waitcnt lgkmcnt(0)
	s_setprio 1
	s_waitcnt lgkmcnt(3)
	v_mfma_f32_16x16x32_bf16 v[28:31], v[200:203], v[48:51], v[28:31]
	s_waitcnt lgkmcnt(1)
	v_mfma_f32_16x16x32_bf16 v[24:27], v[242:245], v[48:51], v[24:27]
	v_mfma_f32_16x16x32_bf16 v[20:23], v[200:203], v[72:75], v[20:23]
	v_mfma_f32_16x16x32_bf16 v[16:19], v[242:245], v[72:75], v[16:19]
	v_mfma_f32_16x16x32_bf16 v[12:15], v[200:203], v[218:221], v[12:15]
	v_mfma_f32_16x16x32_bf16 v[8:11], v[242:245], v[218:221], v[8:11]
	v_mfma_f32_16x16x32_bf16 v[4:7], v[200:203], v[234:237], v[4:7]
	v_mfma_f32_16x16x32_bf16 v[0:3], v[242:245], v[234:237], v[0:3]
	v_mfma_f32_16x16x32_bf16 v[124:127], v[204:207], v[52:55], v[28:31]
	s_waitcnt lgkmcnt(0)
	v_mfma_f32_16x16x32_bf16 v[120:123], v[246:249], v[52:55], v[24:27]
	v_mfma_f32_16x16x32_bf16 v[104:107], v[204:207], v[88:91], v[20:23]
	v_mfma_f32_16x16x32_bf16 v[108:111], v[246:249], v[88:91], v[16:19]
	v_mfma_f32_16x16x32_bf16 v[88:91], v[204:207], v[222:225], v[12:15]
	v_mfma_f32_16x16x32_bf16 v[92:95], v[246:249], v[222:225], v[8:11]
	v_mfma_f32_16x16x32_bf16 v[72:75], v[204:207], v[238:241], v[4:7]
	v_mfma_f32_16x16x32_bf16 v[76:79], v[246:249], v[238:241], v[0:3]
	s_setprio 0
	s_barrier
	ds_read_b128 v[8:11], v180 offset:49152
	ds_read_b128 v[12:15], v180 offset:50176
	ds_read_b128 v[24:27], v181 offset:49152
	ds_read_b128 v[28:31], v181 offset:50176
	ds_read_b128 v[218:221], v182 offset:49152
	ds_read_b128 v[222:225], v182 offset:50176
	ds_read_b128 v[234:237], v183 offset:49152
	ds_read_b128 v[238:241], v183 offset:50176
	s_barrier
	s_waitcnt lgkmcnt(0)
	s_setprio 1
	s_waitcnt lgkmcnt(7)
	v_mfma_f32_16x16x32_bf16 v[0:3], v[172:175], v[8:11], v[32:35]
	s_waitcnt lgkmcnt(6)
	v_mfma_f32_16x16x32_bf16 v[48:51], v[188:191], v[12:15], v[0:3]
	v_mfma_f32_16x16x32_bf16 v[0:3], v[192:195], v[8:11], v[36:39]
	v_mfma_f32_16x16x32_bf16 v[52:55], v[196:199], v[12:15], v[0:3]
	s_waitcnt lgkmcnt(5)
	v_mfma_f32_16x16x32_bf16 v[0:3], v[172:175], v[24:27], v[40:43]
	s_waitcnt lgkmcnt(4)
	v_mfma_f32_16x16x32_bf16 v[32:35], v[188:191], v[28:31], v[0:3]
	v_mfma_f32_16x16x32_bf16 v[0:3], v[192:195], v[24:27], v[44:47]
	v_mfma_f32_16x16x32_bf16 v[36:39], v[196:199], v[28:31], v[0:3]
	s_waitcnt lgkmcnt(3)
	v_mfma_f32_16x16x32_bf16 v[0:3], v[172:175], v[218:221], v[226:229]
	s_waitcnt lgkmcnt(2)
	v_mfma_f32_16x16x32_bf16 v[16:19], v[188:191], v[222:225], v[0:3]
	v_mfma_f32_16x16x32_bf16 v[0:3], v[192:195], v[218:221], v[230:233]
	v_mfma_f32_16x16x32_bf16 v[20:23], v[196:199], v[222:225], v[0:3]
	s_waitcnt lgkmcnt(1)
	v_mfma_f32_16x16x32_bf16 v[0:3], v[172:175], v[234:237], v[60:63]
	v_mfma_f32_16x16x32_bf16 v[4:7], v[192:195], v[234:237], v[128:131]
	s_waitcnt lgkmcnt(0)
	v_mfma_f32_16x16x32_bf16 v[0:3], v[188:191], v[238:241], v[0:3]
	v_mfma_f32_16x16x32_bf16 v[4:7], v[196:199], v[238:241], v[4:7]
	s_setprio 0
	s_setprio 1
	v_mfma_f32_16x16x32_bf16 v[40:43], v[200:203], v[8:11], v[56:59]
	v_mfma_f32_16x16x32_bf16 v[8:11], v[242:245], v[8:11], v[132:135]
	v_mfma_f32_16x16x32_bf16 v[60:63], v[246:249], v[12:15], v[8:11]
	v_mfma_f32_16x16x32_bf16 v[8:11], v[200:203], v[24:27], v[136:139]
	v_mfma_f32_16x16x32_bf16 v[56:59], v[204:207], v[12:15], v[40:43]
	v_mfma_f32_16x16x32_bf16 v[40:43], v[204:207], v[28:31], v[8:11]
	v_mfma_f32_16x16x32_bf16 v[8:11], v[242:245], v[24:27], v[140:143]
	v_mfma_f32_16x16x32_bf16 v[44:47], v[246:249], v[28:31], v[8:11]
	v_mfma_f32_16x16x32_bf16 v[8:11], v[200:203], v[218:221], v[156:159]
	v_mfma_f32_16x16x32_bf16 v[24:27], v[204:207], v[222:225], v[8:11]
	v_mfma_f32_16x16x32_bf16 v[8:11], v[242:245], v[218:221], v[160:163]
	v_mfma_f32_16x16x32_bf16 v[28:31], v[246:249], v[222:225], v[8:11]
	v_mfma_f32_16x16x32_bf16 v[8:11], v[200:203], v[234:237], v[164:167]
	v_mfma_f32_16x16x32_bf16 v[12:15], v[242:245], v[234:237], v[168:171]
	v_mfma_f32_16x16x32_bf16 v[8:11], v[204:207], v[238:241], v[8:11]
	v_mfma_f32_16x16x32_bf16 v[12:15], v[246:249], v[238:241], v[12:15]
	s_setprio 0
	s_barrier
	s_mov_b64 s[6:7], exec
	v_readlane_b32 s2, v250, 10
	v_readlane_b32 s3, v250, 11
	s_and_b64 s[2:3], s[6:7], s[2:3]
	s_mov_b64 exec, s[2:3]
	s_cbranch_execz .LBB0_204
	s_barrier
